# v25 + layer-0 w_down conversion moved from phase 0b into A(0) on WGs 128-255
# speedup vs baseline: 1.0046x; 1.0023x over previous
.Lmy_cvt0:
	v_readlane_b32 s0, v252, 47
	v_readlane_b32 s1, v252, 48
	s_andn2_b64 vcc, exec, s[0:1]
	s_cbranch_vccnz .LBB0_368
	s_cmp_lt_u32 s2, 0x80
	s_cbranch_scc1 .LBB0_368
	s_bfe_i64 s[0:1], s[52:53], 0x200000
	v_readlane_b32 s72, v252, 61
	s_lshl_b64 s[0:1], s[0:1], 13
	v_readlane_b32 s82, v253, 7
	v_readlane_b32 s83, v253, 8
	s_add_u32 s0, s82, s0
	s_addc_u32 s1, s83, s1
	s_mov_b64 s[6:7], s[38:39]
	v_readlane_b32 s36, v254, 50
	s_add_u32 s4, s0, 0xffffe000
	v_readlane_b32 s44, v254, 58
	v_readlane_b32 s80, v253, 5
	s_addc_u32 s5, s1, -1
	s_lshl_b64 s[0:1], s[52:53], 26
	s_lshl_b64 s[12:13], s[52:53], 13
	s_lshl_b64 s[18:19], s[52:53], 24
	s_lshl_b32 s16, s52, 4
	s_lshl_b64 s[20:21], s[52:53], 22
	v_readlane_b32 s38, v254, 52
	v_readlane_b32 s39, v254, 53
	s_lshl_b32 s44, s52, 9
	v_readlane_b32 s81, v253, 6
	s_mov_b64 s[38:39], s[6:7]
	s_add_u32 s6, s80, s0
	v_readlane_b32 s78, v253, 3
	s_addc_u32 s7, s81, s1
	v_readlane_b32 s79, v253, 4
	s_add_u32 s8, s78, s0
	v_readlane_b32 s74, v252, 63
	v_readlane_b32 s40, v254, 54
	s_addc_u32 s9, s79, s1
	v_readlane_b32 s75, v253, 0
	v_readlane_b32 s37, v254, 51
	v_readlane_b32 s41, v254, 55
	s_add_u32 s40, s74, s12
	v_readlane_b32 s42, v254, 56
	s_addc_u32 s41, s75, s13
	s_mov_b32 s1, s37
	v_readlane_b32 s73, v252, 62
	v_readlane_b32 s76, v253, 1
	v_readlane_b32 s77, v253, 2
	v_readlane_b32 s43, v254, 57
	v_readlane_b32 s45, v254, 59
	v_readlane_b32 s46, v254, 60
	v_readlane_b32 s47, v254, 61
	v_readlane_b32 s48, v254, 62
	v_readlane_b32 s49, v254, 63
	s_add_u32 s42, s72, s18
	v_writelane_b32 v254, s0, 50
	s_addc_u32 s43, s73, s19
	v_readlane_b32 s68, v252, 6
	v_writelane_b32 v254, s1, 51
	v_readlane_b32 s84, v253, 9
	v_readlane_b32 s85, v253, 10
	v_readlane_b32 s86, v253, 11
	v_readlane_b32 s87, v253, 12
	v_readlane_b32 s72, v252, 10
	v_readlane_b32 s73, v252, 11
	v_readlane_b32 s74, v252, 12
	v_readlane_b32 s75, v252, 13
	v_readlane_b32 s76, v252, 14
	v_readlane_b32 s77, v252, 15
	v_readlane_b32 s78, v252, 16
	v_readlane_b32 s79, v252, 17
	v_readlane_b32 s80, v252, 18
	v_readlane_b32 s81, v252, 19
	v_readlane_b32 s82, v252, 20
	v_readlane_b32 s83, v252, 21
	v_writelane_b32 v254, s2, 52
	v_writelane_b32 v254, s3, 53
	v_readlane_b32 s72, v252, 22
	v_writelane_b32 v254, s4, 54
	v_readlane_b32 s73, v252, 23
	v_readlane_b32 s74, v252, 24
	v_readlane_b32 s75, v252, 25
	v_readlane_b32 s76, v252, 26
	v_readlane_b32 s77, v252, 27
	v_readlane_b32 s78, v252, 28
	v_readlane_b32 s79, v252, 29
	v_readlane_b32 s80, v252, 30
	v_readlane_b32 s81, v252, 31
	v_readlane_b32 s82, v252, 32
	v_readlane_b32 s83, v252, 33
	v_readlane_b32 s50, v255, 0
	v_readlane_b32 s51, v255, 1
	s_mov_b32 s45, s37
	v_readlane_b32 s69, v252, 7
	s_add_u32 s46, s68, s20
	v_writelane_b32 v254, s5, 55
	v_writelane_b32 v255, s14, 0
	v_readlane_b32 s84, v252, 34
	v_readlane_b32 s85, v252, 35
	v_readlane_b32 s86, v252, 36
	v_readlane_b32 s87, v252, 37
	s_mov_b64 s[72:73], s[76:77]
	s_addc_u32 s47, s69, s21
	v_writelane_b32 v254, s6, 56
	v_writelane_b32 v255, s15, 1
	s_lshl_b64 s[0:1], s[44:45], 2
	s_mov_b64 s[74:75], s[78:79]
	s_mov_b64 s[76:77], s[80:81]
	s_mov_b64 s[78:79], s[82:83]
	s_mov_b64 s[80:81], s[84:85]
	v_writelane_b32 v254, s7, 57
	s_add_u32 s48, s80, s0
	s_mul_i32 s22, s52, 0x300000
	v_writelane_b32 v254, s8, 58
	s_mov_b64 s[82:83], s[86:87]
	s_addc_u32 s49, s81, s1
	s_mul_hi_u32 s17, s52, 0x300000
	v_writelane_b32 v254, s9, 59
	s_add_u32 s50, s82, s22
	v_writelane_b32 v254, s10, 60
	s_addc_u32 s51, s83, s17
	v_writelane_b32 v254, s11, 61
	s_add_u32 s58, s78, s0
	v_readlane_b32 s70, v252, 8
	v_writelane_b32 v254, s12, 62
	s_addc_u32 s59, s79, s1
	s_mul_i32 s1, s52, 0x1880000
	v_readlane_b32 s71, v252, 9
	v_writelane_b32 v254, s13, 63
	s_mul_hi_u32 s0, s52, 0x1880000
	s_add_u32 s70, s76, s1
	s_addc_u32 s71, s77, s0
	s_movk_i32 s17, 0x4000
	s_movk_i32 s18, 0x100
	v_readlane_b32 s19, v254, 38
	v_readlane_b32 s20, v254, 36
	v_readlane_b32 s21, v254, 32
	v_readlane_b32 s22, v252, 46
	s_nop 3
	s_addk_i32 s19, 0xf500
	s_addk_i32 s20, 0xd400
	s_add_i32 s21, s21, 0xfffd4000
	s_addk_i32 s22, 0xfa80
	s_branch .LBB0_269
